# M6 + G_in/G_up: 6th LDS-DMA of the second epoch issued in the third epoch (5/3 instead of 6/2 per loader block), wait2 vmcnt(7)
# baseline (speedup 1.0000x reference)
; #define PG8_SB(B) __builtin_amdgcn_rcpf(1.f + expneg(B))
; #define PG8_SB(B) __builtin_amdgcn_rcpf(1.f + expneg(B))
; #define PG8_STAGE(bufoff, gbase, voff) do { _Pragma("unroll") for (int _i = 0; _i < 2; ++_i) \
;         __builtin_amdgcn_global_load_lds((const unsigned*)((const char*)(gbase) + (size_t)_i * qstep + (voff)[0]), (PG8_LAS unsigned*)(lds + (bufoff) + ldsw + _i * 8192), 16, 0, 0); } while (0)
; #define PG8_LDA(dst, b, h) do { _Pragma("unroll") for (int m = 0; m < 4; ++m) _Pragma("unroll") for (int k = 0; k < 2; ++k) dst[m][k] = *(const PG8_LAS bf16x8*)(lds + PG8_SA(b, h) + aoff + m * 2048 + k * 1024); } while (0)
; #define PG8_MMA(ai, bj, At, Bt) do { __builtin_amdgcn_s_setprio(1); _Pragma("unroll") for (int m = 0; m < 4; ++m) _Pragma("unroll") for (int n = 0; n < 2; ++n) _Pragma("unroll") for (int k = 0; k < 2; ++k) \
;         acc[ai][bj][m][n] = __builtin_amdgcn_mfma_f32_16x16x32_bf16(Bt[n][k], At[m][k], acc[ai][bj][m][n], 0, 0, 0); __builtin_amdgcn_s_setprio(0); } while (0)
; #define PG8_WAIT_V89() do { if constexpr (SLIVER) PG8_WAIT_V(9); else PG8_WAIT_V(8); } while (0)
; #define PG8_LDS_S(b) do { if constexpr (SLIVER) { Sf[0] = *(const PG8_LAS bf16x8*)(lds + STAGE_BYTES + (b) * 2048 + soff0); Sf[1] = *(const PG8_LAS bf16x8*)(lds + STAGE_BYTES + (b) * 2048 + (soff0 ^ 64)); } } while (0)
; #define PG8_WAIT_L(n) asm volatile("s_waitcnt lgkmcnt(" #n ")" ::: "memory")
; #define PG8_BAR __builtin_amdgcn_s_barrier()
; #define PG8_SCHED __builtin_amdgcn_sched_barrier(0)
; template <class Epi, class Sched, bool ALIGN_EPI = false, bool SP2 = false, bool SLIVER = false>
; __device__ __forceinline__ void gemm_phase(PG8_LAS unsigned char* lds, const Gemm g, const Sched& S, const Epi& E) {
;     ...
;             PG8_WAIT_V89(); PG8_WAIT_L(0); PG8_BAR; PG8_MMA(0, 0, At, B0); PG8_MMA(0, 1, At, B1); PG8_BAR; PG8_SCHED;
;             PG8_LDA(At, 0, 1); PG8_LDS_S(0); PG8_STAGE(PG8_SB(0, 0), b2, voffB); PG8_STAGE(PG8_SB(0, 1), b2 + hstep, voffB); PG8_STAGE(PG8_SA(0, 0), a2, voffA);
;             PG8_WAIT_V89(); PG8_WAIT_L(0); PG8_BAR; PG8_MMA(1, 0, At, B0); PG8_MMA(1, 1, At, B1); PG8_MMA_S(); PG8_BAR; PG8_SCHED;
.Lgin_skipw0:
	s_waitcnt lgkmcnt(0)
	s_setprio 1
	s_barrier
	v_mfma_f32_16x16x32_bf16 v[126:129], v[136:139], v[174:177], v[126:129]
	v_mfma_f32_16x16x32_bf16 v[122:125], v[150:153], v[174:177], v[122:125]
	v_mfma_f32_16x16x32_bf16 v[114:117], v[136:139], v[184:187], v[114:117]
	v_mfma_f32_16x16x32_bf16 v[106:109], v[150:153], v[184:187], v[106:109]
	v_mfma_f32_16x16x32_bf16 v[98:101], v[136:139], v[192:195], v[98:101]
	v_mfma_f32_16x16x32_bf16 v[90:93], v[150:153], v[192:195], v[90:93]
	v_mfma_f32_16x16x32_bf16 v[82:85], v[136:139], v[200:203], v[82:85]
	v_mfma_f32_16x16x32_bf16 v[74:77], v[150:153], v[200:203], v[74:77]
	v_mfma_f32_16x16x32_bf16 v[126:129], v[140:143], v[180:183], v[126:129]
	v_mfma_f32_16x16x32_bf16 v[122:125], v[154:157], v[180:183], v[122:125]
	v_mfma_f32_16x16x32_bf16 v[114:117], v[140:143], v[188:191], v[114:117]
	v_mfma_f32_16x16x32_bf16 v[106:109], v[154:157], v[188:191], v[106:109]
	v_mfma_f32_16x16x32_bf16 v[98:101], v[140:143], v[196:199], v[98:101]
	v_mfma_f32_16x16x32_bf16 v[90:93], v[154:157], v[196:199], v[90:93]
	v_mfma_f32_16x16x32_bf16 v[82:85], v[140:143], v[210:213], v[82:85]
	v_mfma_f32_16x16x32_bf16 v[74:77], v[154:157], v[210:213], v[74:77]
	s_setprio 0
	s_setprio 1
	v_mfma_f32_16x16x32_bf16 v[118:121], v[158:161], v[174:177], v[118:121]
	v_mfma_f32_16x16x32_bf16 v[110:113], v[166:169], v[174:177], v[110:113]
	v_mfma_f32_16x16x32_bf16 v[102:105], v[158:161], v[184:187], v[102:105]
	v_mfma_f32_16x16x32_bf16 v[94:97], v[166:169], v[184:187], v[94:97]
	v_mfma_f32_16x16x32_bf16 v[86:89], v[158:161], v[192:195], v[86:89]
	v_mfma_f32_16x16x32_bf16 v[78:81], v[166:169], v[192:195], v[78:81]
	v_mfma_f32_16x16x32_bf16 v[70:73], v[158:161], v[200:203], v[70:73]
	v_mfma_f32_16x16x32_bf16 v[66:69], v[166:169], v[200:203], v[66:69]
	v_mfma_f32_16x16x32_bf16 v[118:121], v[162:165], v[180:183], v[118:121]
	v_mfma_f32_16x16x32_bf16 v[110:113], v[170:173], v[180:183], v[110:113]
	v_mfma_f32_16x16x32_bf16 v[102:105], v[162:165], v[188:191], v[102:105]
	v_mfma_f32_16x16x32_bf16 v[94:97], v[170:173], v[188:191], v[94:97]
	v_mfma_f32_16x16x32_bf16 v[86:89], v[162:165], v[196:199], v[86:89]
	v_mfma_f32_16x16x32_bf16 v[78:81], v[170:173], v[196:199], v[78:81]
	v_mfma_f32_16x16x32_bf16 v[70:73], v[162:165], v[210:213], v[70:73]
	v_mfma_f32_16x16x32_bf16 v[66:69], v[170:173], v[210:213], v[66:69]
	s_barrier
	s_setprio 0
	s_add_i32 s77, s77, s53
	s_mov_b32 m0, s77
	ds_read_b128 v[174:177], v149 offset:16384
	ds_read_b128 v[180:183], v149 offset:17408
	ds_read_b128 v[184:187], v149 offset:18432
	ds_read_b128 v[188:191], v149 offset:19456
	ds_read_b128 v[192:195], v149 offset:20480
	ds_read_b128 v[196:199], v149 offset:21504
	ds_read_b128 v[200:203], v149 offset:22528
	ds_read_b128 v[210:213], v149 offset:23552
	global_load_lds_dwordx4 v132, s[78:79]
	s_add_i32 m0, s77, 0x2000
	s_add_i32 s77, s80, s53
	s_add_u32 s58, s78, 0x40000
	s_addc_u32 s59, s79, 0
	global_load_lds_dwordx4 v132, s[58:59]
	s_mov_b32 m0, s77
	s_nop 0
	s_add_u32 s60, s78, 0x80000
	s_addc_u32 s61, s79, 0
	global_load_lds_dwordx4 v132, s[60:61]
	s_add_i32 m0, s77, 0x2000
	s_nop 0
	s_add_u32 s36, s78, 0xc0000
	s_addc_u32 s37, s79, 0
	global_load_lds_dwordx4 v132, s[36:37]
	s_mov_b64 s[46:47], s[62:63]
	s_mov_b32 m0, s91
	s_nop 0
	global_load_lds_dwordx4 v130, s[46:47]
	s_cmp_eq_u32 s76, s101
	s_cbranch_scc1 .Lgin_skipw1
	s_waitcnt vmcnt(7)
.Lgin_skipw1:
	s_waitcnt lgkmcnt(0)
	s_setprio 1
	s_barrier
	v_mfma_f32_16x16x32_bf16 v[62:65], v[136:139], v[174:177], v[62:65]
	v_mfma_f32_16x16x32_bf16 v[58:61], v[150:153], v[174:177], v[58:61]
	v_mfma_f32_16x16x32_bf16 v[50:53], v[136:139], v[184:187], v[50:53]
	v_mfma_f32_16x16x32_bf16 v[42:45], v[150:153], v[184:187], v[42:45]
	v_mfma_f32_16x16x32_bf16 v[34:37], v[136:139], v[192:195], v[34:37]
	v_mfma_f32_16x16x32_bf16 v[26:29], v[150:153], v[192:195], v[26:29]
	v_mfma_f32_16x16x32_bf16 v[18:21], v[136:139], v[200:203], v[18:21]
	v_mfma_f32_16x16x32_bf16 v[10:13], v[150:153], v[200:203], v[10:13]
	v_mfma_f32_16x16x32_bf16 v[62:65], v[140:143], v[180:183], v[62:65]
	v_mfma_f32_16x16x32_bf16 v[58:61], v[154:157], v[180:183], v[58:61]
	v_mfma_f32_16x16x32_bf16 v[50:53], v[140:143], v[188:191], v[50:53]
	v_mfma_f32_16x16x32_bf16 v[42:45], v[154:157], v[188:191], v[42:45]
	v_mfma_f32_16x16x32_bf16 v[34:37], v[140:143], v[196:199], v[34:37]
	v_mfma_f32_16x16x32_bf16 v[26:29], v[154:157], v[196:199], v[26:29]
	v_mfma_f32_16x16x32_bf16 v[18:21], v[140:143], v[210:213], v[18:21]
	v_mfma_f32_16x16x32_bf16 v[10:13], v[154:157], v[210:213], v[10:13]
	s_setprio 0
	s_setprio 1
	v_mfma_f32_16x16x32_bf16 v[54:57], v[158:161], v[174:177], v[54:57]
	v_mfma_f32_16x16x32_bf16 v[46:49], v[166:169], v[174:177], v[46:49]
	v_mfma_f32_16x16x32_bf16 v[38:41], v[158:161], v[184:187], v[38:41]
	v_mfma_f32_16x16x32_bf16 v[30:33], v[166:169], v[184:187], v[30:33]
	v_mfma_f32_16x16x32_bf16 v[22:25], v[158:161], v[192:195], v[22:25]
	v_mfma_f32_16x16x32_bf16 v[14:17], v[166:169], v[192:195], v[14:17]
	v_mfma_f32_16x16x32_bf16 v[6:9], v[158:161], v[200:203], v[6:9]
	v_mfma_f32_16x16x32_bf16 v[2:5], v[166:169], v[200:203], v[2:5]
	v_mfma_f32_16x16x32_bf16 v[54:57], v[162:165], v[180:183], v[54:57]
	v_mfma_f32_16x16x32_bf16 v[46:49], v[170:173], v[180:183], v[46:49]
	v_mfma_f32_16x16x32_bf16 v[38:41], v[162:165], v[188:191], v[38:41]
	v_mfma_f32_16x16x32_bf16 v[30:33], v[170:173], v[188:191], v[30:33]
	v_mfma_f32_16x16x32_bf16 v[22:25], v[162:165], v[196:199], v[22:25]
	v_mfma_f32_16x16x32_bf16 v[14:17], v[170:173], v[196:199], v[14:17]
	v_mfma_f32_16x16x32_bf16 v[6:9], v[162:165], v[210:213], v[6:9]
	v_mfma_f32_16x16x32_bf16 v[2:5], v[170:173], v[210:213], v[2:5]
	s_barrier
; #define PG8_STAGE(bufoff, gbase, voff) do { _Pragma("unroll") for (int _i = 0; _i < 2; ++_i) \
;         __builtin_amdgcn_global_load_lds((const unsigned*)((const char*)(gbase) + (size_t)_i * qstep + (voff)[0]), (PG8_LAS unsigned*)(lds + (bufoff) + ldsw + _i * 8192), 16, 0, 0); } while (0)
; #define PG8_LDA(dst, b, h) do { _Pragma("unroll") for (int m = 0; m < 4; ++m) _Pragma("unroll") for (int k = 0; k < 2; ++k) dst[m][k] = *(const PG8_LAS bf16x8*)(lds + PG8_SA(b, h) + aoff + m * 2048 + k * 1024); } while (0)
; #define PG8_LDB(dst, b, h) do { _Pragma("unroll") for (int n = 0; n < 2; ++n) _Pragma("unroll") for (int k = 0; k < 2; ++k) dst[n][k] = *(const PG8_LAS bf16x8*)(lds + PG8_SB(b, h) + boff + n * 2048 + k * 1024); } while (0)
; #define PG8_MMA(ai, bj, At, Bt) do { __builtin_amdgcn_s_setprio(1); _Pragma("unroll") for (int m = 0; m < 4; ++m) _Pragma("unroll") for (int n = 0; n < 2; ++n) _Pragma("unroll") for (int k = 0; k < 2; ++k) \
;         acc[ai][bj][m][n] = __builtin_amdgcn_mfma_f32_16x16x32_bf16(Bt[n][k], At[m][k], acc[ai][bj][m][n], 0, 0, 0); __builtin_amdgcn_s_setprio(0); } while (0)
; #define PG8_WAIT_V89() do { if constexpr (SLIVER) PG8_WAIT_V(9); else PG8_WAIT_V(8); } while (0)
; #define PG8_STAGE_S(b, gbase) do { if constexpr (SLIVER) __builtin_amdgcn_global_load_lds((const unsigned*)((const char*)(gbase) + voffS), (PG8_LAS unsigned*)(lds + STAGE_BYTES + (b) * 2048 + wid * 256), 4, 0, 0); } while (0)
; #define PG8_WAIT_L(n) asm volatile("s_waitcnt lgkmcnt(" #n ")" ::: "memory")
; #define PG8_BAR __builtin_amdgcn_s_barrier()
; #define PG8_SCHED __builtin_amdgcn_sched_barrier(0)
; template <class Epi, class Sched, bool ALIGN_EPI = false, bool SP2 = false, bool SLIVER = false>
; __device__ __forceinline__ void gemm_phase(PG8_LAS unsigned char* lds, const Gemm g, const Sched& S, const Epi& E) {
;     ...
;             PG8_WAIT_V89(); PG8_WAIT_L(0); PG8_BAR; PG8_MMA(1, 0, At, B0); PG8_MMA(1, 1, At, B1); PG8_MMA_S(); PG8_BAR; PG8_SCHED;
;             PG8_LDB(B0, 1, 0); PG8_LDB(B1, 1, 1); PG8_SCHED; PG8_LDA(At, 1, 0); PG8_STAGE(PG8_SA(0, 1), a2 + hstep, voffA); PG8_STAGE_S(0, s2);
;             PG8_WAIT_V89(); PG8_WAIT_L(0); PG8_BAR; PG8_MMA(0, 0, At, B0); PG8_MMA(0, 1, At, B1); PG8_BAR; PG8_SCHED;
	s_setprio 0
	s_add_i32 s62, 0, 0x18000
	v_add_u32_e32 v144, s62, v145
	s_add_i32 s63, 0, 0x1c000
	ds_read_b128 v[136:139], v144
	ds_read_b128 v[140:143], v144 offset:1024
	ds_read_b128 v[150:153], v144 offset:2048
	ds_read_b128 v[154:157], v144 offset:3072
	v_add_u32_e32 v144, s63, v145
	ds_read_b128 v[158:161], v144
	ds_read_b128 v[162:165], v144 offset:1024
	ds_read_b128 v[166:169], v144 offset:2048
	ds_read_b128 v[170:173], v144 offset:3072
	s_mov_b32 m0, s51
	ds_read_b128 v[174:177], v149 offset:32768
	ds_read_b128 v[180:183], v149 offset:33792
	ds_read_b128 v[184:187], v149 offset:34816
	ds_read_b128 v[188:191], v149 offset:35840
	ds_read_b128 v[192:195], v149 offset:36864
	ds_read_b128 v[196:199], v149 offset:37888
	ds_read_b128 v[200:203], v149 offset:38912
	ds_read_b128 v[210:213], v149 offset:39936
	s_mov_b32 m0, s50
	s_nop 0
	s_add_u32 s58, s46, 0x40000
	s_addc_u32 s59, s47, 0
	global_load_lds_dwordx4 v130, s[58:59]
	s_mov_b32 m0, s51
	s_nop 0
	s_add_u32 s60, s46, 0x80000
	s_addc_u32 s61, s47, 0
	global_load_lds_dwordx4 v130, s[60:61]
	s_mov_b32 m0, s54
	s_nop 0
	s_add_u32 s36, s46, 0xc0000
	s_addc_u32 s37, s47, 0
	global_load_lds_dwordx4 v130, s[36:37]
	s_waitcnt vmcnt(8)
	s_waitcnt lgkmcnt(0)
	s_setprio 1
	s_barrier
	v_mfma_f32_16x16x32_bf16 v[126:129], v[136:139], v[174:177], v[126:129]
	v_mfma_f32_16x16x32_bf16 v[122:125], v[150:153], v[174:177], v[122:125]
	v_mfma_f32_16x16x32_bf16 v[114:117], v[136:139], v[184:187], v[114:117]
	v_mfma_f32_16x16x32_bf16 v[106:109], v[150:153], v[184:187], v[106:109]
	v_mfma_f32_16x16x32_bf16 v[98:101], v[136:139], v[192:195], v[98:101]
	v_mfma_f32_16x16x32_bf16 v[90:93], v[150:153], v[192:195], v[90:93]
	v_mfma_f32_16x16x32_bf16 v[82:85], v[136:139], v[200:203], v[82:85]
	v_mfma_f32_16x16x32_bf16 v[74:77], v[150:153], v[200:203], v[74:77]
	v_mfma_f32_16x16x32_bf16 v[126:129], v[140:143], v[180:183], v[126:129]
	v_mfma_f32_16x16x32_bf16 v[122:125], v[154:157], v[180:183], v[122:125]
	v_mfma_f32_16x16x32_bf16 v[114:117], v[140:143], v[188:191], v[114:117]
	v_mfma_f32_16x16x32_bf16 v[106:109], v[154:157], v[188:191], v[106:109]
	v_mfma_f32_16x16x32_bf16 v[98:101], v[140:143], v[196:199], v[98:101]
	v_mfma_f32_16x16x32_bf16 v[90:93], v[154:157], v[196:199], v[90:93]
	v_mfma_f32_16x16x32_bf16 v[82:85], v[140:143], v[210:213], v[82:85]
	v_mfma_f32_16x16x32_bf16 v[74:77], v[154:157], v[210:213], v[74:77]
	s_setprio 0
	s_setprio 1
	v_mfma_f32_16x16x32_bf16 v[118:121], v[158:161], v[174:177], v[118:121]
	v_mfma_f32_16x16x32_bf16 v[110:113], v[166:169], v[174:177], v[110:113]
	v_mfma_f32_16x16x32_bf16 v[102:105], v[158:161], v[184:187], v[102:105]
	v_mfma_f32_16x16x32_bf16 v[94:97], v[166:169], v[184:187], v[94:97]
	v_mfma_f32_16x16x32_bf16 v[86:89], v[158:161], v[192:195], v[86:89]
	v_mfma_f32_16x16x32_bf16 v[78:81], v[166:169], v[192:195], v[78:81]
	v_mfma_f32_16x16x32_bf16 v[70:73], v[158:161], v[200:203], v[70:73]
	v_mfma_f32_16x16x32_bf16 v[66:69], v[166:169], v[200:203], v[66:69]
	v_mfma_f32_16x16x32_bf16 v[118:121], v[162:165], v[180:183], v[118:121]
	v_mfma_f32_16x16x32_bf16 v[110:113], v[170:173], v[180:183], v[110:113]
	v_mfma_f32_16x16x32_bf16 v[102:105], v[162:165], v[188:191], v[102:105]
	v_mfma_f32_16x16x32_bf16 v[94:97], v[170:173], v[188:191], v[94:97]
	v_mfma_f32_16x16x32_bf16 v[86:89], v[162:165], v[196:199], v[86:89]
	v_mfma_f32_16x16x32_bf16 v[78:81], v[170:173], v[196:199], v[78:81]
	v_mfma_f32_16x16x32_bf16 v[70:73], v[162:165], v[210:213], v[70:73]
	v_mfma_f32_16x16x32_bf16 v[66:69], v[170:173], v[210:213], v[66:69]
	s_barrier
; #define PG8_SB(B) __builtin_amdgcn_rcpf(1.f + expneg(B))
; #define PG8_SB(B) __builtin_amdgcn_rcpf(1.f + expneg(B))
; #define PG8_STAGE(bufoff, gbase, voff) do { _Pragma("unroll") for (int _i = 0; _i < 2; ++_i) \
;         __builtin_amdgcn_global_load_lds((const unsigned*)((const char*)(gbase) + (size_t)_i * qstep + (voff)[0]), (PG8_LAS unsigned*)(lds + (bufoff) + ldsw + _i * 8192), 16, 0, 0); } while (0)
; #define PG8_LDA(dst, b, h) do { _Pragma("unroll") for (int m = 0; m < 4; ++m) _Pragma("unroll") for (int k = 0; k < 2; ++k) dst[m][k] = *(const PG8_LAS bf16x8*)(lds + PG8_SA(b, h) + aoff + m * 2048 + k * 1024); } while (0)
; #define PG8_MMA(ai, bj, At, Bt) do { __builtin_amdgcn_s_setprio(1); _Pragma("unroll") for (int m = 0; m < 4; ++m) _Pragma("unroll") for (int n = 0; n < 2; ++n) _Pragma("unroll") for (int k = 0; k < 2; ++k) \
;         acc[ai][bj][m][n] = __builtin_amdgcn_mfma_f32_16x16x32_bf16(Bt[n][k], At[m][k], acc[ai][bj][m][n], 0, 0, 0); __builtin_amdgcn_s_setprio(0); } while (0)
; #define PG8_WAIT_V89() do { if constexpr (SLIVER) PG8_WAIT_V(9); else PG8_WAIT_V(8); } while (0)
; #define PG8_LDS_S(b) do { if constexpr (SLIVER) { Sf[0] = *(const PG8_LAS bf16x8*)(lds + STAGE_BYTES + (b) * 2048 + soff0); Sf[1] = *(const PG8_LAS bf16x8*)(lds + STAGE_BYTES + (b) * 2048 + (soff0 ^ 64)); } } while (0)
; #define PG8_WAIT_L(n) asm volatile("s_waitcnt lgkmcnt(" #n ")" ::: "memory")
; #define PG8_BAR __builtin_amdgcn_s_barrier()
; #define PG8_SCHED __builtin_amdgcn_sched_barrier(0)
; template <class Epi, class Sched, bool ALIGN_EPI = false, bool SP2 = false, bool SLIVER = false>
; __device__ __forceinline__ void gemm_phase(PG8_LAS unsigned char* lds, const Gemm g, const Sched& S, const Epi& E) {
;     ...
;             PG8_WAIT_V89(); PG8_WAIT_L(0); PG8_BAR; PG8_MMA(0, 0, At, B0); PG8_MMA(0, 1, At, B1); PG8_BAR; PG8_SCHED;
;             PG8_LDA(At, 1, 1); PG8_LDS_S(1); PG8_STAGE(PG8_SB(1, 0), b3, voffB); PG8_STAGE(PG8_SB(1, 1), b3 + hstep, voffB); PG8_STAGE(PG8_SA(1, 0), a3, voffA);
;             PG8_WAIT_V89(); PG8_WAIT_L(0); PG8_BAR; PG8_MMA(1, 0, At, B0); PG8_MMA(1, 1, At, B1); PG8_MMA_S(); PG8_BAR; PG8_SCHED;
;     ...
;         if constexpr (ALIGN_EPI) { if (wr == 0) PG8_BAR; }
	s_setprio 0
	s_add_i32 s62, s62, s53
	s_mov_b32 m0, s62
	ds_read_b128 v[174:177], v149 offset:49152
	ds_read_b128 v[180:183], v149 offset:50176
	ds_read_b128 v[184:187], v149 offset:51200
	ds_read_b128 v[188:191], v149 offset:52224
	ds_read_b128 v[192:195], v149 offset:53248
	ds_read_b128 v[196:199], v149 offset:54272
	ds_read_b128 v[200:203], v149 offset:55296
	ds_read_b128 v[210:213], v149 offset:56320
	s_add_u32 s58, s78, 0x80
	s_addc_u32 s59, s79, 0
	global_load_lds_dwordx4 v132, s[58:59]
	s_add_i32 m0, s62, 0x2000
	s_add_i32 s62, s63, s53
	s_add_u32 s60, s78, 0x40080
	s_addc_u32 s61, s79, 0
	global_load_lds_dwordx4 v132, s[60:61]
	s_mov_b32 m0, s62
	s_add_u32 s36, s78, 0x80080
	s_addc_u32 s37, s79, 0
	global_load_lds_dwordx4 v132, s[36:37]
	s_add_i32 m0, s62, 0x2000
	s_nop 0
	s_add_u32 s58, s78, 0xc0080
	s_addc_u32 s59, s79, 0
	global_load_lds_dwordx4 v132, s[58:59]
	s_mov_b32 m0, s10
	s_nop 0
	s_add_u32 s60, s46, 0x80
	s_addc_u32 s61, s47, 0
	global_load_lds_dwordx4 v130, s[60:61]
	s_mov_b32 m0, s55
	s_nop 0
	s_add_u32 s36, s46, 0x40080
	s_addc_u32 s37, s47, 0
	global_load_lds_dwordx4 v130, s[36:37]
	s_waitcnt vmcnt(8)
	s_waitcnt lgkmcnt(0)
	s_setprio 1
	s_barrier
	v_mfma_f32_16x16x32_bf16 v[62:65], v[136:139], v[174:177], v[62:65]
	v_mfma_f32_16x16x32_bf16 v[58:61], v[150:153], v[174:177], v[58:61]
	v_mfma_f32_16x16x32_bf16 v[50:53], v[136:139], v[184:187], v[50:53]
	v_mfma_f32_16x16x32_bf16 v[42:45], v[150:153], v[184:187], v[42:45]
	v_mfma_f32_16x16x32_bf16 v[34:37], v[136:139], v[192:195], v[34:37]
	v_mfma_f32_16x16x32_bf16 v[26:29], v[150:153], v[192:195], v[26:29]
	v_mfma_f32_16x16x32_bf16 v[18:21], v[136:139], v[200:203], v[18:21]
	v_mfma_f32_16x16x32_bf16 v[10:13], v[150:153], v[200:203], v[10:13]
	v_mfma_f32_16x16x32_bf16 v[62:65], v[140:143], v[180:183], v[62:65]
	v_mfma_f32_16x16x32_bf16 v[58:61], v[154:157], v[180:183], v[58:61]
	v_mfma_f32_16x16x32_bf16 v[50:53], v[140:143], v[188:191], v[50:53]
	v_mfma_f32_16x16x32_bf16 v[42:45], v[154:157], v[188:191], v[42:45]
	v_mfma_f32_16x16x32_bf16 v[34:37], v[140:143], v[196:199], v[34:37]
	v_mfma_f32_16x16x32_bf16 v[26:29], v[154:157], v[196:199], v[26:29]
	v_mfma_f32_16x16x32_bf16 v[18:21], v[140:143], v[210:213], v[18:21]
	v_mfma_f32_16x16x32_bf16 v[10:13], v[154:157], v[210:213], v[10:13]
	s_setprio 0
	s_setprio 1
	v_mfma_f32_16x16x32_bf16 v[54:57], v[158:161], v[174:177], v[54:57]
	v_mfma_f32_16x16x32_bf16 v[46:49], v[166:169], v[174:177], v[46:49]
	v_mfma_f32_16x16x32_bf16 v[38:41], v[158:161], v[184:187], v[38:41]
	v_mfma_f32_16x16x32_bf16 v[30:33], v[166:169], v[184:187], v[30:33]
	v_mfma_f32_16x16x32_bf16 v[22:25], v[158:161], v[192:195], v[22:25]
	v_mfma_f32_16x16x32_bf16 v[14:17], v[166:169], v[192:195], v[14:17]
	v_mfma_f32_16x16x32_bf16 v[6:9], v[158:161], v[200:203], v[6:9]
	v_mfma_f32_16x16x32_bf16 v[2:5], v[166:169], v[200:203], v[2:5]
	v_mfma_f32_16x16x32_bf16 v[54:57], v[162:165], v[180:183], v[54:57]
	v_mfma_f32_16x16x32_bf16 v[46:49], v[170:173], v[180:183], v[46:49]
	v_mfma_f32_16x16x32_bf16 v[38:41], v[162:165], v[188:191], v[38:41]
	v_mfma_f32_16x16x32_bf16 v[30:33], v[170:173], v[188:191], v[30:33]
	v_mfma_f32_16x16x32_bf16 v[22:25], v[162:165], v[196:199], v[22:25]
	v_mfma_f32_16x16x32_bf16 v[14:17], v[170:173], v[196:199], v[14:17]
	v_mfma_f32_16x16x32_bf16 v[6:9], v[162:165], v[210:213], v[6:9]
	v_mfma_f32_16x16x32_bf16 v[2:5], v[170:173], v[210:213], v[2:5]
	s_barrier
	s_setprio 0
	s_add_i32 s76, s76, 2
	s_add_u32 s40, s40, 0x100
	s_addc_u32 s41, s41, 0
	s_add_u32 s68, s68, 0x100
	s_addc_u32 s69, s69, 0
	s_cmp_gt_u32 s76, 29
	s_cbranch_scc0 .LBB0_153
	s_and_b64 vcc, exec, s[48:49]
	s_cbranch_vccz .LBB0_156
	s_barrier

; #define PG8_SB(B) __builtin_amdgcn_rcpf(1.f + expneg(B))
; #define PG8_SB(B) __builtin_amdgcn_rcpf(1.f + expneg(B))
; #define PG8_STAGE(bufoff, gbase, voff) do { _Pragma("unroll") for (int _i = 0; _i < 2; ++_i) \
;         __builtin_amdgcn_global_load_lds((const unsigned*)((const char*)(gbase) + (size_t)_i * qstep + (voff)[0]), (PG8_LAS unsigned*)(lds + (bufoff) + ldsw + _i * 8192), 16, 0, 0); } while (0)
; #define PG8_LDA(dst, b, h) do { _Pragma("unroll") for (int m = 0; m < 4; ++m) _Pragma("unroll") for (int k = 0; k < 2; ++k) dst[m][k] = *(const PG8_LAS bf16x8*)(lds + PG8_SA(b, h) + aoff + m * 2048 + k * 1024); } while (0)
; #define PG8_MMA(ai, bj, At, Bt) do { __builtin_amdgcn_s_setprio(1); _Pragma("unroll") for (int m = 0; m < 4; ++m) _Pragma("unroll") for (int n = 0; n < 2; ++n) _Pragma("unroll") for (int k = 0; k < 2; ++k) \
;         acc[ai][bj][m][n] = __builtin_amdgcn_mfma_f32_16x16x32_bf16(Bt[n][k], At[m][k], acc[ai][bj][m][n], 0, 0, 0); __builtin_amdgcn_s_setprio(0); } while (0)
; #define PG8_WAIT_V89() do { if constexpr (SLIVER) PG8_WAIT_V(9); else PG8_WAIT_V(8); } while (0)
; #define PG8_LDS_S(b) do { if constexpr (SLIVER) { Sf[0] = *(const PG8_LAS bf16x8*)(lds + STAGE_BYTES + (b) * 2048 + soff0); Sf[1] = *(const PG8_LAS bf16x8*)(lds + STAGE_BYTES + (b) * 2048 + (soff0 ^ 64)); } } while (0)
; #define PG8_WAIT_L(n) asm volatile("s_waitcnt lgkmcnt(" #n ")" ::: "memory")
; #define PG8_BAR __builtin_amdgcn_s_barrier()
; #define PG8_SCHED __builtin_amdgcn_sched_barrier(0)
; template <class Epi, class Sched, bool ALIGN_EPI = false, bool SP2 = false, bool SLIVER = false>
; __device__ __forceinline__ void gemm_phase(PG8_LAS unsigned char* lds, const Gemm g, const Sched& S, const Epi& E) {
;     ...
;             PG8_WAIT_V89(); PG8_WAIT_L(0); PG8_BAR; PG8_MMA(0, 0, At, B0); PG8_MMA(0, 1, At, B1); PG8_BAR; PG8_SCHED;
;             PG8_LDA(At, 0, 1); PG8_LDS_S(0); PG8_STAGE(PG8_SB(0, 0), b2, voffB); PG8_STAGE(PG8_SB(0, 1), b2 + hstep, voffB); PG8_STAGE(PG8_SA(0, 0), a2, voffA);
;             PG8_WAIT_V89(); PG8_WAIT_L(0); PG8_BAR; PG8_MMA(1, 0, At, B0); PG8_MMA(1, 1, At, B1); PG8_MMA_S(); PG8_BAR; PG8_SCHED;
.Lgup_skipw0:
	s_waitcnt lgkmcnt(0)
	s_setprio 1
	s_barrier
	v_mfma_f32_16x16x32_bf16 v[126:129], v[130:133], v[172:175], v[126:129]
	v_mfma_f32_16x16x32_bf16 v[118:121], v[148:151], v[172:175], v[118:121]
	v_mfma_f32_16x16x32_bf16 v[110:113], v[130:133], v[184:187], v[110:113]
	v_mfma_f32_16x16x32_bf16 v[102:105], v[148:151], v[184:187], v[102:105]
	v_mfma_f32_16x16x32_bf16 v[94:97], v[130:133], v[192:195], v[94:97]
	v_mfma_f32_16x16x32_bf16 v[86:89], v[148:151], v[192:195], v[86:89]
	v_mfma_f32_16x16x32_bf16 v[78:81], v[130:133], v[200:203], v[78:81]
	v_mfma_f32_16x16x32_bf16 v[70:73], v[148:151], v[200:203], v[70:73]
	v_mfma_f32_16x16x32_bf16 v[126:129], v[138:141], v[180:183], v[126:129]
	v_mfma_f32_16x16x32_bf16 v[118:121], v[152:155], v[180:183], v[118:121]
	v_mfma_f32_16x16x32_bf16 v[110:113], v[138:141], v[188:191], v[110:113]
	v_mfma_f32_16x16x32_bf16 v[102:105], v[152:155], v[188:191], v[102:105]
	v_mfma_f32_16x16x32_bf16 v[94:97], v[138:141], v[196:199], v[94:97]
	v_mfma_f32_16x16x32_bf16 v[86:89], v[152:155], v[196:199], v[86:89]
	v_mfma_f32_16x16x32_bf16 v[78:81], v[138:141], v[210:213], v[78:81]
	v_mfma_f32_16x16x32_bf16 v[70:73], v[152:155], v[210:213], v[70:73]
	s_setprio 0
	s_setprio 1
	v_mfma_f32_16x16x32_bf16 v[122:125], v[156:159], v[172:175], v[122:125]
	v_mfma_f32_16x16x32_bf16 v[114:117], v[164:167], v[172:175], v[114:117]
	v_mfma_f32_16x16x32_bf16 v[106:109], v[156:159], v[184:187], v[106:109]
	v_mfma_f32_16x16x32_bf16 v[98:101], v[164:167], v[184:187], v[98:101]
	v_mfma_f32_16x16x32_bf16 v[90:93], v[156:159], v[192:195], v[90:93]
	v_mfma_f32_16x16x32_bf16 v[82:85], v[164:167], v[192:195], v[82:85]
	v_mfma_f32_16x16x32_bf16 v[74:77], v[156:159], v[200:203], v[74:77]
	v_mfma_f32_16x16x32_bf16 v[66:69], v[164:167], v[200:203], v[66:69]
	v_mfma_f32_16x16x32_bf16 v[122:125], v[160:163], v[180:183], v[122:125]
	v_mfma_f32_16x16x32_bf16 v[114:117], v[168:171], v[180:183], v[114:117]
	v_mfma_f32_16x16x32_bf16 v[106:109], v[160:163], v[188:191], v[106:109]
	v_mfma_f32_16x16x32_bf16 v[98:101], v[168:171], v[188:191], v[98:101]
	v_mfma_f32_16x16x32_bf16 v[90:93], v[160:163], v[196:199], v[90:93]
	v_mfma_f32_16x16x32_bf16 v[82:85], v[168:171], v[196:199], v[82:85]
	v_mfma_f32_16x16x32_bf16 v[74:77], v[160:163], v[210:213], v[74:77]
	v_mfma_f32_16x16x32_bf16 v[66:69], v[168:171], v[210:213], v[66:69]
	s_barrier
	s_setprio 0
	s_mov_b64 s[46:47], s[76:77]
	s_add_i32 s76, s78, s88
	s_mov_b32 m0, s76
	ds_read_b128 v[172:175], v147 offset:16384
	ds_read_b128 v[180:183], v147 offset:17408
	ds_read_b128 v[184:187], v147 offset:18432
	ds_read_b128 v[188:191], v147 offset:19456
	ds_read_b128 v[192:195], v147 offset:20480
	ds_read_b128 v[196:199], v147 offset:21504
	ds_read_b128 v[200:203], v147 offset:22528
	ds_read_b128 v[210:213], v147 offset:23552
	global_load_lds_dwordx4 v178, s[46:47]
	s_add_i32 m0, s76, 0x2000
	s_add_i32 s76, s79, s88
	s_add_u32 s58, s46, 0x40000
	s_addc_u32 s59, s47, 0
	global_load_lds_dwordx4 v178, s[58:59]
	s_mov_b32 m0, s76
	s_nop 0
	s_add_u32 s60, s46, 0x80000
	s_addc_u32 s61, s47, 0
	global_load_lds_dwordx4 v178, s[60:61]
	s_add_i32 m0, s76, 0x2000
	s_nop 0
	s_add_u32 s36, s46, 0xc0000
	s_addc_u32 s37, s47, 0
	global_load_lds_dwordx4 v178, s[36:37]
	s_mov_b32 m0, s45
	s_nop 0
	global_load_lds_dwordx4 v134, s[80:81]
	s_cmp_eq_u32 s69, s101
	s_cbranch_scc1 .Lgup_skipw1
	s_waitcnt vmcnt(7)
.Lgup_skipw1:
	s_waitcnt lgkmcnt(0)
	s_setprio 1
	s_barrier
	v_mfma_f32_16x16x32_bf16 v[62:65], v[130:133], v[172:175], v[62:65]
	v_mfma_f32_16x16x32_bf16 v[54:57], v[148:151], v[172:175], v[54:57]
	v_mfma_f32_16x16x32_bf16 v[46:49], v[130:133], v[184:187], v[46:49]
	v_mfma_f32_16x16x32_bf16 v[38:41], v[148:151], v[184:187], v[38:41]
	v_mfma_f32_16x16x32_bf16 v[30:33], v[130:133], v[192:195], v[30:33]
	v_mfma_f32_16x16x32_bf16 v[22:25], v[148:151], v[192:195], v[22:25]
	v_mfma_f32_16x16x32_bf16 v[14:17], v[130:133], v[200:203], v[14:17]
	v_mfma_f32_16x16x32_bf16 v[6:9], v[148:151], v[200:203], v[6:9]
	v_mfma_f32_16x16x32_bf16 v[62:65], v[138:141], v[180:183], v[62:65]
	v_mfma_f32_16x16x32_bf16 v[54:57], v[152:155], v[180:183], v[54:57]
	v_mfma_f32_16x16x32_bf16 v[46:49], v[138:141], v[188:191], v[46:49]
	v_mfma_f32_16x16x32_bf16 v[38:41], v[152:155], v[188:191], v[38:41]
	v_mfma_f32_16x16x32_bf16 v[30:33], v[138:141], v[196:199], v[30:33]
	v_mfma_f32_16x16x32_bf16 v[22:25], v[152:155], v[196:199], v[22:25]
	v_mfma_f32_16x16x32_bf16 v[14:17], v[138:141], v[210:213], v[14:17]
	v_mfma_f32_16x16x32_bf16 v[6:9], v[152:155], v[210:213], v[6:9]
	s_setprio 0
	s_setprio 1
	v_mfma_f32_16x16x32_bf16 v[58:61], v[156:159], v[172:175], v[58:61]
	v_mfma_f32_16x16x32_bf16 v[50:53], v[164:167], v[172:175], v[50:53]
	v_mfma_f32_16x16x32_bf16 v[42:45], v[156:159], v[184:187], v[42:45]
	v_mfma_f32_16x16x32_bf16 v[34:37], v[164:167], v[184:187], v[34:37]
	v_mfma_f32_16x16x32_bf16 v[26:29], v[156:159], v[192:195], v[26:29]
	v_mfma_f32_16x16x32_bf16 v[18:21], v[164:167], v[192:195], v[18:21]
	v_mfma_f32_16x16x32_bf16 v[10:13], v[156:159], v[200:203], v[10:13]
	v_mfma_f32_16x16x32_bf16 v[2:5], v[164:167], v[200:203], v[2:5]
	v_mfma_f32_16x16x32_bf16 v[58:61], v[160:163], v[180:183], v[58:61]
	v_mfma_f32_16x16x32_bf16 v[50:53], v[168:171], v[180:183], v[50:53]
	v_mfma_f32_16x16x32_bf16 v[42:45], v[160:163], v[188:191], v[42:45]
	v_mfma_f32_16x16x32_bf16 v[34:37], v[168:171], v[188:191], v[34:37]
	v_mfma_f32_16x16x32_bf16 v[26:29], v[160:163], v[196:199], v[26:29]
	v_mfma_f32_16x16x32_bf16 v[18:21], v[168:171], v[196:199], v[18:21]
	v_mfma_f32_16x16x32_bf16 v[10:13], v[160:163], v[210:213], v[10:13]
	v_mfma_f32_16x16x32_bf16 v[2:5], v[168:171], v[210:213], v[2:5]
	s_barrier
; #define PG8_STAGE(bufoff, gbase, voff) do { _Pragma("unroll") for (int _i = 0; _i < 2; ++_i) \
;         __builtin_amdgcn_global_load_lds((const unsigned*)((const char*)(gbase) + (size_t)_i * qstep + (voff)[0]), (PG8_LAS unsigned*)(lds + (bufoff) + ldsw + _i * 8192), 16, 0, 0); } while (0)
; #define PG8_LDA(dst, b, h) do { _Pragma("unroll") for (int m = 0; m < 4; ++m) _Pragma("unroll") for (int k = 0; k < 2; ++k) dst[m][k] = *(const PG8_LAS bf16x8*)(lds + PG8_SA(b, h) + aoff + m * 2048 + k * 1024); } while (0)
; #define PG8_LDB(dst, b, h) do { _Pragma("unroll") for (int n = 0; n < 2; ++n) _Pragma("unroll") for (int k = 0; k < 2; ++k) dst[n][k] = *(const PG8_LAS bf16x8*)(lds + PG8_SB(b, h) + boff + n * 2048 + k * 1024); } while (0)
; #define PG8_MMA(ai, bj, At, Bt) do { __builtin_amdgcn_s_setprio(1); _Pragma("unroll") for (int m = 0; m < 4; ++m) _Pragma("unroll") for (int n = 0; n < 2; ++n) _Pragma("unroll") for (int k = 0; k < 2; ++k) \
;         acc[ai][bj][m][n] = __builtin_amdgcn_mfma_f32_16x16x32_bf16(Bt[n][k], At[m][k], acc[ai][bj][m][n], 0, 0, 0); __builtin_amdgcn_s_setprio(0); } while (0)
; #define PG8_WAIT_V89() do { if constexpr (SLIVER) PG8_WAIT_V(9); else PG8_WAIT_V(8); } while (0)
; #define PG8_STAGE_S(b, gbase) do { if constexpr (SLIVER) __builtin_amdgcn_global_load_lds((const unsigned*)((const char*)(gbase) + voffS), (PG8_LAS unsigned*)(lds + STAGE_BYTES + (b) * 2048 + wid * 256), 4, 0, 0); } while (0)
; #define PG8_WAIT_L(n) asm volatile("s_waitcnt lgkmcnt(" #n ")" ::: "memory")
; #define PG8_BAR __builtin_amdgcn_s_barrier()
; #define PG8_SCHED __builtin_amdgcn_sched_barrier(0)
; template <class Epi, class Sched, bool ALIGN_EPI = false, bool SP2 = false, bool SLIVER = false>
; __device__ __forceinline__ void gemm_phase(PG8_LAS unsigned char* lds, const Gemm g, const Sched& S, const Epi& E) {
;     ...
;             PG8_WAIT_V89(); PG8_WAIT_L(0); PG8_BAR; PG8_MMA(1, 0, At, B0); PG8_MMA(1, 1, At, B1); PG8_MMA_S(); PG8_BAR; PG8_SCHED;
;             PG8_LDB(B0, 1, 0); PG8_LDB(B1, 1, 1); PG8_SCHED; PG8_LDA(At, 1, 0); PG8_STAGE(PG8_SA(0, 1), a2 + hstep, voffA); PG8_STAGE_S(0, s2);
;             PG8_WAIT_V89(); PG8_WAIT_L(0); PG8_BAR; PG8_MMA(0, 0, At, B0); PG8_MMA(0, 1, At, B1); PG8_BAR; PG8_SCHED;
	s_setprio 0
	s_add_i32 s76, 0, 0x18000
	v_add_u32_e32 v142, s76, v143
	s_add_i32 s77, 0, 0x1c000
	ds_read_b128 v[130:133], v142
	ds_read_b128 v[138:141], v142 offset:1024
	ds_read_b128 v[148:151], v142 offset:2048
	ds_read_b128 v[152:155], v142 offset:3072
	v_add_u32_e32 v142, s77, v143
	ds_read_b128 v[156:159], v142
	ds_read_b128 v[160:163], v142 offset:1024
	ds_read_b128 v[164:167], v142 offset:2048
	ds_read_b128 v[168:171], v142 offset:3072
	s_mov_b32 m0, s90
	ds_read_b128 v[172:175], v147 offset:32768
	ds_read_b128 v[180:183], v147 offset:33792
	ds_read_b128 v[184:187], v147 offset:34816
	ds_read_b128 v[188:191], v147 offset:35840
	ds_read_b128 v[192:195], v147 offset:36864
	ds_read_b128 v[196:199], v147 offset:37888
	ds_read_b128 v[200:203], v147 offset:38912
	ds_read_b128 v[210:213], v147 offset:39936
	s_mov_b32 m0, s83
	s_nop 0
	s_add_u32 s58, s80, 0x40000
	s_addc_u32 s59, s81, 0
	global_load_lds_dwordx4 v134, s[58:59]
	s_mov_b32 m0, s90
	s_nop 0
	s_add_u32 s60, s80, 0x80000
	s_addc_u32 s61, s81, 0
	global_load_lds_dwordx4 v134, s[60:61]
	s_mov_b32 m0, s91
	s_nop 0
	s_add_u32 s36, s80, 0xc0000
	s_addc_u32 s37, s81, 0
	global_load_lds_dwordx4 v134, s[36:37]
	s_waitcnt vmcnt(8)
	s_waitcnt lgkmcnt(0)
	s_setprio 1
	s_barrier
	v_mfma_f32_16x16x32_bf16 v[126:129], v[130:133], v[172:175], v[126:129]
	v_mfma_f32_16x16x32_bf16 v[118:121], v[148:151], v[172:175], v[118:121]
	v_mfma_f32_16x16x32_bf16 v[110:113], v[130:133], v[184:187], v[110:113]
	v_mfma_f32_16x16x32_bf16 v[102:105], v[148:151], v[184:187], v[102:105]
	v_mfma_f32_16x16x32_bf16 v[94:97], v[130:133], v[192:195], v[94:97]
	v_mfma_f32_16x16x32_bf16 v[86:89], v[148:151], v[192:195], v[86:89]
	v_mfma_f32_16x16x32_bf16 v[78:81], v[130:133], v[200:203], v[78:81]
	v_mfma_f32_16x16x32_bf16 v[70:73], v[148:151], v[200:203], v[70:73]
	v_mfma_f32_16x16x32_bf16 v[126:129], v[138:141], v[180:183], v[126:129]
	v_mfma_f32_16x16x32_bf16 v[118:121], v[152:155], v[180:183], v[118:121]
	v_mfma_f32_16x16x32_bf16 v[110:113], v[138:141], v[188:191], v[110:113]
	v_mfma_f32_16x16x32_bf16 v[102:105], v[152:155], v[188:191], v[102:105]
	v_mfma_f32_16x16x32_bf16 v[94:97], v[138:141], v[196:199], v[94:97]
	v_mfma_f32_16x16x32_bf16 v[86:89], v[152:155], v[196:199], v[86:89]
	v_mfma_f32_16x16x32_bf16 v[78:81], v[138:141], v[210:213], v[78:81]
	v_mfma_f32_16x16x32_bf16 v[70:73], v[152:155], v[210:213], v[70:73]
	s_setprio 0
	s_setprio 1
	v_mfma_f32_16x16x32_bf16 v[122:125], v[156:159], v[172:175], v[122:125]
	v_mfma_f32_16x16x32_bf16 v[114:117], v[164:167], v[172:175], v[114:117]
	v_mfma_f32_16x16x32_bf16 v[106:109], v[156:159], v[184:187], v[106:109]
	v_mfma_f32_16x16x32_bf16 v[98:101], v[164:167], v[184:187], v[98:101]
	v_mfma_f32_16x16x32_bf16 v[90:93], v[156:159], v[192:195], v[90:93]
	v_mfma_f32_16x16x32_bf16 v[82:85], v[164:167], v[192:195], v[82:85]
	v_mfma_f32_16x16x32_bf16 v[74:77], v[156:159], v[200:203], v[74:77]
	v_mfma_f32_16x16x32_bf16 v[66:69], v[164:167], v[200:203], v[66:69]
	v_mfma_f32_16x16x32_bf16 v[122:125], v[160:163], v[180:183], v[122:125]
	v_mfma_f32_16x16x32_bf16 v[114:117], v[168:171], v[180:183], v[114:117]
	v_mfma_f32_16x16x32_bf16 v[106:109], v[160:163], v[188:191], v[106:109]
	v_mfma_f32_16x16x32_bf16 v[98:101], v[168:171], v[188:191], v[98:101]
	v_mfma_f32_16x16x32_bf16 v[90:93], v[160:163], v[196:199], v[90:93]
	v_mfma_f32_16x16x32_bf16 v[82:85], v[168:171], v[196:199], v[82:85]
	v_mfma_f32_16x16x32_bf16 v[74:77], v[160:163], v[210:213], v[74:77]
	v_mfma_f32_16x16x32_bf16 v[66:69], v[168:171], v[210:213], v[66:69]
	s_barrier
; #define PG8_SB(B) __builtin_amdgcn_rcpf(1.f + expneg(B))
; #define PG8_SB(B) __builtin_amdgcn_rcpf(1.f + expneg(B))
; #define PG8_STAGE(bufoff, gbase, voff) do { _Pragma("unroll") for (int _i = 0; _i < 2; ++_i) \
;         __builtin_amdgcn_global_load_lds((const unsigned*)((const char*)(gbase) + (size_t)_i * qstep + (voff)[0]), (PG8_LAS unsigned*)(lds + (bufoff) + ldsw + _i * 8192), 16, 0, 0); } while (0)
; #define PG8_LDA(dst, b, h) do { _Pragma("unroll") for (int m = 0; m < 4; ++m) _Pragma("unroll") for (int k = 0; k < 2; ++k) dst[m][k] = *(const PG8_LAS bf16x8*)(lds + PG8_SA(b, h) + aoff + m * 2048 + k * 1024); } while (0)
; #define PG8_MMA(ai, bj, At, Bt) do { __builtin_amdgcn_s_setprio(1); _Pragma("unroll") for (int m = 0; m < 4; ++m) _Pragma("unroll") for (int n = 0; n < 2; ++n) _Pragma("unroll") for (int k = 0; k < 2; ++k) \
;         acc[ai][bj][m][n] = __builtin_amdgcn_mfma_f32_16x16x32_bf16(Bt[n][k], At[m][k], acc[ai][bj][m][n], 0, 0, 0); __builtin_amdgcn_s_setprio(0); } while (0)
; #define PG8_WAIT_V89() do { if constexpr (SLIVER) PG8_WAIT_V(9); else PG8_WAIT_V(8); } while (0)
; #define PG8_LDS_S(b) do { if constexpr (SLIVER) { Sf[0] = *(const PG8_LAS bf16x8*)(lds + STAGE_BYTES + (b) * 2048 + soff0); Sf[1] = *(const PG8_LAS bf16x8*)(lds + STAGE_BYTES + (b) * 2048 + (soff0 ^ 64)); } } while (0)
; #define PG8_WAIT_L(n) asm volatile("s_waitcnt lgkmcnt(" #n ")" ::: "memory")
; #define PG8_BAR __builtin_amdgcn_s_barrier()
; #define PG8_SCHED __builtin_amdgcn_sched_barrier(0)
; template <class Epi, class Sched, bool ALIGN_EPI = false, bool SP2 = false, bool SLIVER = false>
; __device__ __forceinline__ void gemm_phase(PG8_LAS unsigned char* lds, const Gemm g, const Sched& S, const Epi& E) {
;     ...
;             PG8_WAIT_V89(); PG8_WAIT_L(0); PG8_BAR; PG8_MMA(0, 0, At, B0); PG8_MMA(0, 1, At, B1); PG8_BAR; PG8_SCHED;
;             PG8_LDA(At, 1, 1); PG8_LDS_S(1); PG8_STAGE(PG8_SB(1, 0), b3, voffB); PG8_STAGE(PG8_SB(1, 1), b3 + hstep, voffB); PG8_STAGE(PG8_SA(1, 0), a3, voffA);
;             PG8_WAIT_V89(); PG8_WAIT_L(0); PG8_BAR; PG8_MMA(1, 0, At, B0); PG8_MMA(1, 1, At, B1); PG8_MMA_S(); PG8_BAR; PG8_SCHED;
;     ...
;         if constexpr (ALIGN_EPI) { if (wr == 0) PG8_BAR; }
	s_setprio 0
	s_add_i32 s76, s76, s88
	s_mov_b32 m0, s76
	ds_read_b128 v[172:175], v147 offset:49152
	ds_read_b128 v[180:183], v147 offset:50176
	ds_read_b128 v[184:187], v147 offset:51200
	ds_read_b128 v[188:191], v147 offset:52224
	ds_read_b128 v[192:195], v147 offset:53248
	ds_read_b128 v[196:199], v147 offset:54272
	ds_read_b128 v[200:203], v147 offset:55296
	ds_read_b128 v[210:213], v147 offset:56320
	s_add_u32 s58, s46, 0x80
	s_addc_u32 s59, s47, 0
	global_load_lds_dwordx4 v178, s[58:59]
	s_add_i32 m0, s76, 0x2000
	s_add_i32 s76, s77, s88
	s_add_u32 s60, s46, 0x40080
	s_addc_u32 s61, s47, 0
	global_load_lds_dwordx4 v178, s[60:61]
	s_mov_b32 m0, s76
	s_add_u32 s36, s46, 0x80080
	s_addc_u32 s37, s47, 0
	global_load_lds_dwordx4 v178, s[36:37]
	s_add_i32 m0, s76, 0x2000
	s_nop 0
	s_add_u32 s58, s46, 0xc0080
	s_addc_u32 s59, s47, 0
	global_load_lds_dwordx4 v178, s[58:59]
	s_mov_b32 m0, s93
	s_nop 0
	s_add_u32 s60, s80, 0x80
	s_addc_u32 s61, s81, 0
	global_load_lds_dwordx4 v134, s[60:61]
	s_mov_b32 m0, s94
	s_nop 0
	s_add_u32 s36, s80, 0x40080
	s_addc_u32 s37, s81, 0
	global_load_lds_dwordx4 v134, s[36:37]
	s_waitcnt vmcnt(8)
	s_waitcnt lgkmcnt(0)
	s_setprio 1
	s_barrier
	v_mfma_f32_16x16x32_bf16 v[62:65], v[130:133], v[172:175], v[62:65]
	v_mfma_f32_16x16x32_bf16 v[54:57], v[148:151], v[172:175], v[54:57]
	v_mfma_f32_16x16x32_bf16 v[46:49], v[130:133], v[184:187], v[46:49]
	v_mfma_f32_16x16x32_bf16 v[38:41], v[148:151], v[184:187], v[38:41]
	v_mfma_f32_16x16x32_bf16 v[30:33], v[130:133], v[192:195], v[30:33]
	v_mfma_f32_16x16x32_bf16 v[22:25], v[148:151], v[192:195], v[22:25]
	v_mfma_f32_16x16x32_bf16 v[14:17], v[130:133], v[200:203], v[14:17]
	v_mfma_f32_16x16x32_bf16 v[6:9], v[148:151], v[200:203], v[6:9]
	v_mfma_f32_16x16x32_bf16 v[62:65], v[138:141], v[180:183], v[62:65]
	v_mfma_f32_16x16x32_bf16 v[54:57], v[152:155], v[180:183], v[54:57]
	v_mfma_f32_16x16x32_bf16 v[46:49], v[138:141], v[188:191], v[46:49]
	v_mfma_f32_16x16x32_bf16 v[38:41], v[152:155], v[188:191], v[38:41]
	v_mfma_f32_16x16x32_bf16 v[30:33], v[138:141], v[196:199], v[30:33]
	v_mfma_f32_16x16x32_bf16 v[22:25], v[152:155], v[196:199], v[22:25]
	v_mfma_f32_16x16x32_bf16 v[14:17], v[138:141], v[210:213], v[14:17]
	v_mfma_f32_16x16x32_bf16 v[6:9], v[152:155], v[210:213], v[6:9]
	s_setprio 0
	s_setprio 1
	v_mfma_f32_16x16x32_bf16 v[58:61], v[156:159], v[172:175], v[58:61]
	v_mfma_f32_16x16x32_bf16 v[50:53], v[164:167], v[172:175], v[50:53]
	v_mfma_f32_16x16x32_bf16 v[42:45], v[156:159], v[184:187], v[42:45]
	v_mfma_f32_16x16x32_bf16 v[34:37], v[164:167], v[184:187], v[34:37]
	v_mfma_f32_16x16x32_bf16 v[26:29], v[156:159], v[192:195], v[26:29]
	v_mfma_f32_16x16x32_bf16 v[18:21], v[164:167], v[192:195], v[18:21]
	v_mfma_f32_16x16x32_bf16 v[10:13], v[156:159], v[200:203], v[10:13]
	v_mfma_f32_16x16x32_bf16 v[2:5], v[164:167], v[200:203], v[2:5]
	v_mfma_f32_16x16x32_bf16 v[58:61], v[160:163], v[180:183], v[58:61]
	v_mfma_f32_16x16x32_bf16 v[50:53], v[168:171], v[180:183], v[50:53]
	v_mfma_f32_16x16x32_bf16 v[42:45], v[160:163], v[188:191], v[42:45]
	v_mfma_f32_16x16x32_bf16 v[34:37], v[168:171], v[188:191], v[34:37]
	v_mfma_f32_16x16x32_bf16 v[26:29], v[160:163], v[196:199], v[26:29]
	v_mfma_f32_16x16x32_bf16 v[18:21], v[168:171], v[196:199], v[18:21]
	v_mfma_f32_16x16x32_bf16 v[10:13], v[160:163], v[210:213], v[10:13]
	v_mfma_f32_16x16x32_bf16 v[2:5], v[168:171], v[210:213], v[2:5]
	s_barrier
	s_setprio 0
	s_add_i32 s69, s69, 2
	s_add_u32 s62, s62, 0x100
	s_addc_u32 s63, s63, 0
	s_add_u32 s67, s67, 0x100
	s_addc_u32 s68, s68, 0
	s_cmp_gt_u32 s69, 29
	s_cbranch_scc0 .LBB0_705
	s_and_b64 vcc, exec, s[42:43]
	s_cbranch_vccz .LBB0_708
	s_barrier
